# grid barrier: the first workgroup of each XCD to arrive starts an L2 write-back while it waits, so the XCD leader's release write-back has little left
# speedup vs baseline: 1.0068x; 1.0010x over previous
.LBB0_367:
	v_readlane_b32 s4, v253, 11
	v_readlane_b32 s5, v253, 12
	v_mov_b32_e32 v1, 1
	v_sub_u32_e32 v4, 0, v2
	s_nop 2
	global_atomic_add v3, v145, v1, s[4:5] sc0
	v_cvt_f32_u32_e32 v1, v2
	v_rcp_iflag_f32_e32 v1, v1
	s_nop 0
	v_mul_f32_e32 v1, 0x4f7ffffe, v1
	v_cvt_u32_f32_e32 v1, v1
	v_mul_lo_u32 v4, v4, v1
	v_mul_hi_u32 v4, v1, v4
	v_add_u32_e32 v1, v1, v4
	s_waitcnt vmcnt(0)
	v_mul_hi_u32 v1, v3, v1
	v_mul_lo_u32 v4, v1, v2
	v_sub_u32_e32 v4, v3, v4
	v_add_u32_e32 v5, 1, v1
	v_cmp_ge_u32_e32 vcc, v4, v2
	v_add_u32_e32 v3, 1, v3
	s_nop 0
	v_cndmask_b32_e32 v1, v1, v5, vcc
	v_sub_u32_e32 v5, v4, v2
	v_cndmask_b32_e32 v4, v4, v5, vcc
	v_add_u32_e32 v5, 1, v1
	v_cmp_ge_u32_e32 vcc, v4, v2
	s_nop 1
	v_cndmask_b32_e32 v1, v1, v5, vcc
	v_mul_lo_u32 v4, v2, v1
	v_add_u32_e32 v2, v4, v2
	v_cmp_ne_u32_e32 vcc, v3, v2
	s_and_saveexec_b64 s[4:5], vcc
	s_xor_b64 s[4:5], exec, s[4:5]
	s_cbranch_execz .LBB0_381
	v_add_u32_e32 v4, 1, v4
	v_cmp_eq_u32_e32 vcc, v3, v4
	s_cbranch_vccz .Lff_0
	buffer_wbl2 sc1
.Lff_0:
	v_readlane_b32 s6, v253, 17
	v_readlane_b32 s7, v253, 18
	s_waitcnt lgkmcnt(0)
	s_nop 3
	global_load_dword v0, v145, s[6:7] sc1
	s_waitcnt vmcnt(0)
	v_cmp_eq_u32_e32 vcc, v0, v1
	s_and_saveexec_b64 s[6:7], vcc
	s_cbranch_execz .LBB0_380
	s_mov_b32 s17, 1
	s_mov_b64 s[44:45], 0
	s_branch .LBB0_371

.Lff_5:
	v_readlane_b32 s6, v253, 17
	v_readlane_b32 s7, v253, 18
	s_waitcnt lgkmcnt(0)
	s_nop 3
	global_load_dword v0, v145, s[6:7] sc1
	s_waitcnt vmcnt(0)
	v_cmp_eq_u32_e32 vcc, v0, v1
	s_and_saveexec_b64 s[6:7], vcc
	s_cbranch_execz .LBB0_1024
	s_mov_b32 s17, 1
	s_mov_b64 s[42:43], 0
	s_branch .LBB0_1015

.Lff_6:
	v_readlane_b32 s6, v253, 17
	v_readlane_b32 s7, v253, 18
	s_waitcnt lgkmcnt(0)
	s_nop 3
	global_load_dword v0, v145, s[6:7] sc1
	s_waitcnt vmcnt(0)
	v_cmp_eq_u32_e32 vcc, v0, v1
	s_and_saveexec_b64 s[6:7], vcc
	s_cbranch_execz .LBB0_1084
	s_mov_b32 s16, 1
	s_mov_b64 s[42:43], 0
	s_branch .LBB0_1075

.LBB0_1242:
	v_readlane_b32 s6, v253, 11
	v_mov_b32_e32 v3, 0
	v_mov_b32_e32 v1, 1
	v_readlane_b32 s7, v253, 12
	v_sub_u32_e32 v5, 0, v2
	s_nop 3
	global_atomic_add v4, v3, v1, s[6:7] sc0
	v_cvt_f32_u32_e32 v1, v2
	v_rcp_iflag_f32_e32 v1, v1
	s_nop 0
	v_mul_f32_e32 v1, 0x4f7ffffe, v1
	v_cvt_u32_f32_e32 v1, v1
	v_mul_lo_u32 v5, v5, v1
	v_mul_hi_u32 v5, v1, v5
	v_add_u32_e32 v1, v1, v5
	s_waitcnt vmcnt(0)
	v_mul_hi_u32 v1, v4, v1
	v_mul_lo_u32 v5, v1, v2
	v_sub_u32_e32 v5, v4, v5
	v_add_u32_e32 v6, 1, v1
	v_cmp_ge_u32_e32 vcc, v5, v2
	v_add_u32_e32 v4, 1, v4
	s_nop 0
	v_cndmask_b32_e32 v1, v1, v6, vcc
	v_sub_u32_e32 v6, v5, v2
	v_cndmask_b32_e32 v5, v5, v6, vcc
	v_add_u32_e32 v6, 1, v1
	v_cmp_ge_u32_e32 vcc, v5, v2
	s_nop 1
	v_cndmask_b32_e32 v1, v1, v6, vcc
	v_mul_lo_u32 v5, v2, v1
	v_add_u32_e32 v2, v5, v2
	v_cmp_ne_u32_e32 vcc, v4, v2
	s_and_saveexec_b64 s[6:7], vcc
	s_xor_b64 s[6:7], exec, s[6:7]
	s_cbranch_execz .LBB0_1256
	v_add_u32_e32 v5, 1, v5
	v_cmp_eq_u32_e32 vcc, v4, v5
	s_cbranch_vccz .Lff_7
	buffer_wbl2 sc1
.Lff_7:
	v_readlane_b32 s8, v253, 17
	v_readlane_b32 s9, v253, 18
	s_waitcnt lgkmcnt(0)
	s_nop 3
	global_load_dword v0, v3, s[8:9] sc1
	s_waitcnt vmcnt(0)
	v_cmp_eq_u32_e32 vcc, v0, v1
	s_and_saveexec_b64 s[8:9], vcc
	s_cbranch_execz .LBB0_1255
	s_mov_b32 s20, 1
	s_mov_b64 s[10:11], 0
	v_mov_b32_e32 v0, 0
	s_branch .LBB0_1246

.LBB0_1308:
	v_readlane_b32 s4, v253, 11
	v_mov_b32_e32 v3, 0
	v_mov_b32_e32 v1, 1
	v_readlane_b32 s5, v253, 12
	v_sub_u32_e32 v5, 0, v2
	s_nop 3
	global_atomic_add v4, v3, v1, s[4:5] sc0
	v_cvt_f32_u32_e32 v1, v2
	v_rcp_iflag_f32_e32 v1, v1
	s_nop 0
	v_mul_f32_e32 v1, 0x4f7ffffe, v1
	v_cvt_u32_f32_e32 v1, v1
	v_mul_lo_u32 v5, v5, v1
	v_mul_hi_u32 v5, v1, v5
	v_add_u32_e32 v1, v1, v5
	s_waitcnt vmcnt(0)
	v_mul_hi_u32 v1, v4, v1
	v_mul_lo_u32 v5, v1, v2
	v_sub_u32_e32 v5, v4, v5
	v_add_u32_e32 v6, 1, v1
	v_cmp_ge_u32_e32 vcc, v5, v2
	v_add_u32_e32 v4, 1, v4
	s_nop 0
	v_cndmask_b32_e32 v1, v1, v6, vcc
	v_sub_u32_e32 v6, v5, v2
	v_cndmask_b32_e32 v5, v5, v6, vcc
	v_add_u32_e32 v6, 1, v1
	v_cmp_ge_u32_e32 vcc, v5, v2
	s_nop 1
	v_cndmask_b32_e32 v1, v1, v6, vcc
	v_mul_lo_u32 v5, v2, v1
	v_add_u32_e32 v2, v5, v2
	v_cmp_ne_u32_e32 vcc, v4, v2
	s_and_saveexec_b64 s[4:5], vcc
	s_xor_b64 s[4:5], exec, s[4:5]
	s_cbranch_execz .LBB0_1322
	v_add_u32_e32 v5, 1, v5
	v_cmp_eq_u32_e32 vcc, v4, v5
	s_cbranch_vccz .Lff_8
	buffer_wbl2 sc1
.Lff_8:
	v_readlane_b32 s6, v253, 17
	v_readlane_b32 s7, v253, 18
	s_waitcnt lgkmcnt(0)
	s_nop 3
	global_load_dword v0, v3, s[6:7] sc1
	s_waitcnt vmcnt(0)
	v_cmp_eq_u32_e32 vcc, v0, v1
	s_and_saveexec_b64 s[6:7], vcc
	s_cbranch_execz .LBB0_1321
	s_mov_b32 s18, 1
	s_mov_b64 s[8:9], 0
	v_mov_b32_e32 v0, 0
	s_branch .LBB0_1312

.LBB0_1550:
	v_readlane_b32 s4, v253, 11
	v_readlane_b32 s5, v253, 12
	v_cvt_f32_u32_e32 v0, v3
	v_sub_u32_e32 v5, 0, v3
	v_rcp_iflag_f32_e32 v0, v0
	s_nop 1
	global_atomic_add v4, v1, v252, s[4:5] sc0
	v_mul_f32_e32 v0, 0x4f7ffffe, v0
	v_cvt_u32_f32_e32 v0, v0
	v_mul_lo_u32 v5, v5, v0
	v_mul_hi_u32 v5, v0, v5
	v_add_u32_e32 v0, v0, v5
	s_waitcnt vmcnt(0)
	v_mul_hi_u32 v0, v4, v0
	v_mul_lo_u32 v5, v0, v3
	v_sub_u32_e32 v5, v4, v5
	v_add_u32_e32 v6, 1, v0
	v_cmp_ge_u32_e32 vcc, v5, v3
	v_add_u32_e32 v4, 1, v4
	s_nop 0
	v_cndmask_b32_e32 v0, v0, v6, vcc
	v_sub_u32_e32 v6, v5, v3
	v_cndmask_b32_e32 v5, v5, v6, vcc
	v_add_u32_e32 v6, 1, v0
	v_cmp_ge_u32_e32 vcc, v5, v3
	s_nop 1
	v_cndmask_b32_e32 v0, v0, v6, vcc
	v_mul_lo_u32 v5, v3, v0
	v_add_u32_e32 v3, v5, v3
	v_cmp_ne_u32_e32 vcc, v4, v3
	s_and_saveexec_b64 s[4:5], vcc
	s_xor_b64 s[4:5], exec, s[4:5]
	s_cbranch_execz .LBB0_1564
	v_add_u32_e32 v5, 1, v5
	v_cmp_eq_u32_e32 vcc, v4, v5
	s_cbranch_vccz .Lff_9
	buffer_wbl2 sc1
.Lff_9:
	v_readlane_b32 s6, v253, 17
	v_readlane_b32 s7, v253, 18
	s_waitcnt lgkmcnt(0)
	s_nop 3
	global_load_dword v2, v1, s[6:7] sc1
	s_waitcnt vmcnt(0)
	v_cmp_eq_u32_e32 vcc, v2, v0
	s_and_saveexec_b64 s[6:7], vcc
	s_cbranch_execz .LBB0_1563
	s_mov_b32 s18, 1
	s_mov_b64 s[8:9], 0
	s_branch .LBB0_1554

.Lff_12:
	v_readlane_b32 s6, v253, 17
	v_readlane_b32 s7, v253, 18
	s_waitcnt lgkmcnt(0)
	s_nop 3
	global_load_dword v2, v1, s[6:7] sc1
	s_waitcnt vmcnt(0)
	v_cmp_eq_u32_e32 vcc, v2, v0
	s_and_saveexec_b64 s[6:7], vcc
	s_cbranch_execz .LBB0_3229
	s_mov_b32 s20, 1
	s_mov_b64 s[10:11], 0
	s_branch .LBB0_3220
